# v044_poolpipe16x2
# baseline (speedup 1.0000x reference)
; __device__ __forceinline__ float bflo(unsigned u) { return __uint_as_float(u << 16); }
; __device__ __forceinline__ float bfhi(unsigned u) { return __uint_as_float(u & 0xffff0000u); }
; #define SCHED __builtin_amdgcn_sched_barrier(0)
; template <int W>
; __device__ __forceinline__ void pool_compute(const Params& p, int layer, int g, int dh, int tt, const int tidx) {
;     ...
;   for (int kb = 0; kb < 4; ++kb) {
;     u32x4 av[4][4];
; #pragma unroll
;     for (int k4 = 0; k4 < 4; ++k4)
; #pragma unroll
;       for (int d = 0; d < 4; ++d)
;         av[k4][d] = *reinterpret_cast<const u32x4*>(wpb + (woff + (unsigned)(((dh * 4 + d) * 32) * 512 + (kb * 4 + k4) * 32)));
;     SCHED;
; #pragma unroll
;     for (int k4 = 0; k4 < 4; ++k4) {
;       const int ks = kb * 4 + k4;
;       float sum[8];
; #pragma unroll
;       for (int j = 0; j < 8; ++j) sum[j] = 0.f;
;       u32x4 x0 = *reinterpret_cast<const u32x4*>(xl + ks * 32);
; #pragma unroll
;       for (int i = 0; i < W; ++i) {
;         u32x4 xv = *reinterpret_cast<const u32x4*>(xl + ks * 32 - i * PXS);
;         sum[0] += bflo(xv.x); sum[1] += bfhi(xv.x); sum[2] += bflo(xv.y); sum[3] += bfhi(xv.y);
;         sum[4] += bflo(xv.z); sum[5] += bfhi(xv.z); sum[6] += bflo(xv.w); sum[7] += bfhi(xv.w);
;       }
.LBB0_185:
	v_add_co_u32_e32 v68, vcc, s13, v136
	s_nop 1
	v_addc_co_u32_e32 v69, vcc, 0, v137, vcc
	v_add_co_u32_e32 v72, vcc, s14, v136
	s_nop 1
	v_addc_co_u32_e32 v73, vcc, 0, v137, vcc
	v_add_co_u32_e32 v76, vcc, s15, v136
	s_nop 1
	v_addc_co_u32_e32 v77, vcc, 0, v137, vcc
	global_load_dwordx4 v[114:117], v[136:137], off
	global_load_dwordx4 v[98:101], v[136:137], off offset:32
	global_load_dwordx4 v[118:121], v[68:69], off
	global_load_dwordx4 v[102:105], v[68:69], off offset:32
	global_load_dwordx4 v[122:125], v[72:73], off
	global_load_dwordx4 v[106:109], v[72:73], off offset:32
	global_load_dwordx4 v[126:129], v[76:77], off
	global_load_dwordx4 v[110:113], v[76:77], off offset:32
	global_load_dwordx4 v[80:83], v[136:137], off offset:64
	global_load_dwordx4 v[64:67], v[136:137], off offset:96
	global_load_dwordx4 v[84:87], v[68:69], off offset:64
	s_nop 0
	global_load_dwordx4 v[68:71], v[68:69], off offset:96
	s_nop 0
	global_load_dwordx4 v[88:91], v[72:73], off offset:64
	s_nop 0
	global_load_dwordx4 v[72:75], v[72:73], off offset:96
	s_nop 0
	global_load_dwordx4 v[92:95], v[76:77], off offset:64
	s_nop 0
	global_load_dwordx4 v[76:79], v[76:77], off offset:96
	v_add_u32_e32 v144, s12, v143
	v_add_u32_e32 v131, 0x141c0, v144
	ds_read_b128 v[150:153], v131
	v_add_u32_e32 v154, 0x13fb0, v144
	ds_read_b128 v[154:157], v154
	v_add_u32_e32 v130, 0x122d0, v144
	s_addk_i32 s12, 0x80
	s_waitcnt lgkmcnt(1)
	v_and_b32_e32 v146, 0xffff0000, v150
	v_add_f32_e32 v132, 0, v146
	v_lshlrev_b32_e32 v147, 16, v151
	s_waitcnt lgkmcnt(0)
	v_lshlrev_b32_e32 v165, 16, v154
	v_and_b32_e32 v154, 0xffff0000, v154
	v_add_f32_e32 v133, 0, v147
	v_and_b32_e32 v148, 0xffff0000, v151
	v_add_f32_e32 v132, v132, v154
	v_lshlrev_b32_e32 v154, 16, v155
	v_add_f32_e32 v158, 0, v148
	v_lshlrev_b32_e32 v149, 16, v152
	v_add_f32_e32 v133, v133, v154
	v_and_b32_e32 v154, 0xffff0000, v155
	v_lshlrev_b32_e32 v145, 16, v150
	v_add_f32_e32 v159, 0, v149
	v_and_b32_e32 v150, 0xffff0000, v152
	v_add_f32_e32 v158, v158, v154
	v_lshlrev_b32_e32 v154, 16, v156
	v_add_f32_e32 v160, 0, v150
	v_lshlrev_b32_e32 v151, 16, v153
	v_add_f32_e32 v159, v159, v154
	v_and_b32_e32 v154, 0xffff0000, v156
	v_add_f32_e32 v161, 0, v151
	v_and_b32_e32 v152, 0xffff0000, v153
	v_add_f32_e32 v160, v160, v154
	v_lshlrev_b32_e32 v154, 16, v157
	v_add_f32_e32 v153, 0, v152
	v_add_f32_e32 v161, v161, v154
	v_and_b32_e32 v154, 0xffff0000, v157
	v_add_f32_e32 v153, v153, v154
	v_add_u32_e32 v154, 0x13da0, v144
	ds_read_b128 v[154:157], v154
	v_add_f32_e32 v131, 0, v145
	v_add_f32_e32 v131, v131, v165
	v_lshl_add_u64 v[136:137], v[136:137], 0, s[16:17]
	s_cmpk_lg_i32 s12, 0x200
	s_waitcnt lgkmcnt(0)
	v_add_u32_e32 v172, 0x13b90, v144
	ds_read_b128 v[172:175], v172
	v_add_u32_e32 v168, 0x13980, v144
	ds_read_b128 v[168:171], v168
	v_lshlrev_b32_e32 v165, 16, v154
	v_and_b32_e32 v154, 0xffff0000, v154
	v_add_f32_e32 v132, v132, v154
	v_lshlrev_b32_e32 v154, 16, v155
	v_add_f32_e32 v133, v133, v154
	v_and_b32_e32 v154, 0xffff0000, v155
	v_add_f32_e32 v158, v158, v154
	v_lshlrev_b32_e32 v154, 16, v156
	v_add_f32_e32 v159, v159, v154
	v_and_b32_e32 v154, 0xffff0000, v156
	v_add_f32_e32 v160, v160, v154
	v_lshlrev_b32_e32 v154, 16, v157
	v_add_f32_e32 v161, v161, v154
	v_and_b32_e32 v154, 0xffff0000, v157
	v_add_f32_e32 v153, v153, v154
	v_add_f32_e32 v131, v131, v165
	s_waitcnt lgkmcnt(1)
	v_add_u32_e32 v154, 0x13770, v144
	ds_read_b128 v[154:157], v154
	v_lshlrev_b32_e32 v165, 16, v172
	v_and_b32_e32 v172, 0xffff0000, v172
	v_add_f32_e32 v132, v132, v172
	v_lshlrev_b32_e32 v172, 16, v173
	v_add_f32_e32 v133, v133, v172
	v_and_b32_e32 v172, 0xffff0000, v173
	v_add_f32_e32 v158, v158, v172
	v_lshlrev_b32_e32 v172, 16, v174
	v_add_f32_e32 v159, v159, v172
	v_and_b32_e32 v172, 0xffff0000, v174
	v_add_f32_e32 v160, v160, v172
	v_lshlrev_b32_e32 v172, 16, v175
	v_add_f32_e32 v161, v161, v172
	v_and_b32_e32 v172, 0xffff0000, v175
	v_add_f32_e32 v153, v153, v172
	v_add_f32_e32 v131, v131, v165
	s_waitcnt lgkmcnt(1)
	v_add_u32_e32 v172, 0x13560, v144
	ds_read_b128 v[172:175], v172
	v_lshlrev_b32_e32 v165, 16, v168
	v_and_b32_e32 v168, 0xffff0000, v168
	v_add_f32_e32 v132, v132, v168
	v_lshlrev_b32_e32 v168, 16, v169
	v_add_f32_e32 v133, v133, v168
	v_and_b32_e32 v168, 0xffff0000, v169
	v_add_f32_e32 v158, v158, v168
	v_lshlrev_b32_e32 v168, 16, v170
	v_add_f32_e32 v159, v159, v168
	v_and_b32_e32 v168, 0xffff0000, v170
	v_add_f32_e32 v160, v160, v168
	v_lshlrev_b32_e32 v168, 16, v171
	v_add_f32_e32 v161, v161, v168
	v_and_b32_e32 v168, 0xffff0000, v171
	v_add_f32_e32 v153, v153, v168
	v_add_f32_e32 v131, v131, v165
	s_waitcnt lgkmcnt(1)
	v_add_u32_e32 v168, 0x13350, v144
	ds_read_b128 v[168:171], v168
	v_lshlrev_b32_e32 v165, 16, v154
	v_and_b32_e32 v154, 0xffff0000, v154
	v_add_f32_e32 v132, v132, v154
	v_lshlrev_b32_e32 v154, 16, v155
	v_add_f32_e32 v133, v133, v154
	v_and_b32_e32 v154, 0xffff0000, v155
	v_add_f32_e32 v158, v158, v154
	v_lshlrev_b32_e32 v154, 16, v156
	v_add_f32_e32 v159, v159, v154
	v_and_b32_e32 v154, 0xffff0000, v156
	v_add_f32_e32 v160, v160, v154
	v_lshlrev_b32_e32 v154, 16, v157
	v_add_f32_e32 v161, v161, v154
	v_and_b32_e32 v154, 0xffff0000, v157
	v_add_f32_e32 v153, v153, v154
	v_add_f32_e32 v131, v131, v165
	s_waitcnt lgkmcnt(1)
	v_add_u32_e32 v154, 0x13140, v144
	ds_read_b128 v[154:157], v154
	v_lshlrev_b32_e32 v165, 16, v172
	v_and_b32_e32 v172, 0xffff0000, v172
	v_add_f32_e32 v132, v132, v172
	v_lshlrev_b32_e32 v172, 16, v173
	v_add_f32_e32 v133, v133, v172
	v_and_b32_e32 v172, 0xffff0000, v173
	v_add_f32_e32 v158, v158, v172
	v_lshlrev_b32_e32 v172, 16, v174
	v_add_f32_e32 v159, v159, v172
	v_and_b32_e32 v172, 0xffff0000, v174
	v_add_f32_e32 v160, v160, v172
	v_lshlrev_b32_e32 v172, 16, v175
	v_add_f32_e32 v161, v161, v172
	v_and_b32_e32 v172, 0xffff0000, v175
	v_add_f32_e32 v153, v153, v172
	v_add_f32_e32 v131, v131, v165
	s_waitcnt lgkmcnt(1)
; __device__ __forceinline__ float bflo(unsigned u) { return __uint_as_float(u << 16); }
; __device__ __forceinline__ float bfhi(unsigned u) { return __uint_as_float(u & 0xffff0000u); }
; template <int W>
; __device__ __forceinline__ void pool_compute(const Params& p, int layer, int g, int dh, int tt, const int tidx) {
;     ...
;       u32x4 x0 = *reinterpret_cast<const u32x4*>(xl + ks * 32);
; #pragma unroll
;       for (int i = 0; i < W; ++i) {
;         u32x4 xv = *reinterpret_cast<const u32x4*>(xl + ks * 32 - i * PXS);
;         sum[0] += bflo(xv.x); sum[1] += bfhi(xv.x); sum[2] += bflo(xv.y); sum[3] += bfhi(xv.y);
;         sum[4] += bflo(xv.z); sum[5] += bfhi(xv.z); sum[6] += bflo(xv.w); sum[7] += bfhi(xv.w);
;       }
;       u32x4 bfr;
;       bfr.x = pack2(sum[0] * inv - bflo(x0.x), sum[1] * inv - bfhi(x0.x));
;       bfr.y = pack2(sum[2] * inv - bflo(x0.y), sum[3] * inv - bfhi(x0.y));
;       bfr.z = pack2(sum[4] * inv - bflo(x0.z), sum[5] * inv - bfhi(x0.z));
;       bfr.w = pack2(sum[6] * inv - bflo(x0.w), sum[7] * inv - bfhi(x0.w));
; #pragma unroll
;       for (int d = 0; d < 4; ++d) acc[d] = __builtin_amdgcn_mfma_f32_32x32x16_bf16(as_bf16x8(av[k4][d]), as_bf16x8(bfr), acc[d], 0, 0, 0);
	v_add_u32_e32 v172, 0x12f30, v144
	ds_read_b128 v[172:175], v172
	v_lshlrev_b32_e32 v165, 16, v168
	v_and_b32_e32 v168, 0xffff0000, v168
	v_add_f32_e32 v132, v132, v168
	v_lshlrev_b32_e32 v168, 16, v169
	v_add_f32_e32 v133, v133, v168
	v_and_b32_e32 v168, 0xffff0000, v169
	v_add_f32_e32 v158, v158, v168
	v_lshlrev_b32_e32 v168, 16, v170
	v_add_f32_e32 v159, v159, v168
	v_and_b32_e32 v168, 0xffff0000, v170
	v_add_f32_e32 v160, v160, v168
	v_lshlrev_b32_e32 v168, 16, v171
	v_add_f32_e32 v161, v161, v168
	v_and_b32_e32 v168, 0xffff0000, v171
	v_add_f32_e32 v153, v153, v168
	v_add_f32_e32 v131, v131, v165
	s_waitcnt lgkmcnt(1)
	v_add_u32_e32 v168, 0x12d20, v144
	ds_read_b128 v[168:171], v168
	v_lshlrev_b32_e32 v165, 16, v154
	v_and_b32_e32 v154, 0xffff0000, v154
	v_add_f32_e32 v132, v132, v154
	v_lshlrev_b32_e32 v154, 16, v155
	v_add_f32_e32 v133, v133, v154
	v_and_b32_e32 v154, 0xffff0000, v155
	v_add_f32_e32 v158, v158, v154
	v_lshlrev_b32_e32 v154, 16, v156
	v_add_f32_e32 v159, v159, v154
	v_and_b32_e32 v154, 0xffff0000, v156
	v_add_f32_e32 v160, v160, v154
	v_lshlrev_b32_e32 v154, 16, v157
	v_add_f32_e32 v161, v161, v154
	v_and_b32_e32 v154, 0xffff0000, v157
	v_add_f32_e32 v153, v153, v154
	v_add_f32_e32 v131, v131, v165
	s_waitcnt lgkmcnt(1)
	v_add_u32_e32 v154, 0x12b10, v144
	ds_read_b128 v[154:157], v154
	v_lshlrev_b32_e32 v165, 16, v172
	v_and_b32_e32 v172, 0xffff0000, v172
	v_add_f32_e32 v132, v132, v172
	v_lshlrev_b32_e32 v172, 16, v173
	v_add_f32_e32 v133, v133, v172
	v_and_b32_e32 v172, 0xffff0000, v173
	v_add_f32_e32 v158, v158, v172
	v_lshlrev_b32_e32 v172, 16, v174
	v_add_f32_e32 v159, v159, v172
	v_and_b32_e32 v172, 0xffff0000, v174
	v_add_f32_e32 v160, v160, v172
	v_lshlrev_b32_e32 v172, 16, v175
	v_add_f32_e32 v161, v161, v172
	v_and_b32_e32 v172, 0xffff0000, v175
	v_add_f32_e32 v153, v153, v172
	v_add_f32_e32 v131, v131, v165
	s_waitcnt lgkmcnt(1)
	v_add_u32_e32 v172, 0x12900, v144
	ds_read_b128 v[172:175], v172
	v_lshlrev_b32_e32 v165, 16, v168
	v_and_b32_e32 v168, 0xffff0000, v168
	v_add_f32_e32 v132, v132, v168
	v_lshlrev_b32_e32 v168, 16, v169
	v_add_f32_e32 v133, v133, v168
	v_and_b32_e32 v168, 0xffff0000, v169
	v_add_f32_e32 v158, v158, v168
	v_lshlrev_b32_e32 v168, 16, v170
	v_add_f32_e32 v159, v159, v168
	v_and_b32_e32 v168, 0xffff0000, v170
	v_add_f32_e32 v160, v160, v168
	v_lshlrev_b32_e32 v168, 16, v171
	v_add_f32_e32 v161, v161, v168
	v_and_b32_e32 v168, 0xffff0000, v171
	v_add_f32_e32 v153, v153, v168
	v_add_f32_e32 v131, v131, v165
	s_waitcnt lgkmcnt(1)
	v_add_u32_e32 v168, 0x126f0, v144
	ds_read_b128 v[168:171], v168
	v_lshlrev_b32_e32 v165, 16, v154
	v_and_b32_e32 v154, 0xffff0000, v154
	v_add_f32_e32 v132, v132, v154
	v_lshlrev_b32_e32 v154, 16, v155
	v_add_f32_e32 v133, v133, v154
	v_and_b32_e32 v154, 0xffff0000, v155
	v_add_f32_e32 v158, v158, v154
	v_lshlrev_b32_e32 v154, 16, v156
	v_add_f32_e32 v159, v159, v154
	v_and_b32_e32 v154, 0xffff0000, v156
	v_add_f32_e32 v160, v160, v154
	v_lshlrev_b32_e32 v154, 16, v157
	v_add_f32_e32 v161, v161, v154
	v_and_b32_e32 v154, 0xffff0000, v157
	v_add_f32_e32 v153, v153, v154
	v_add_f32_e32 v131, v131, v165
	s_waitcnt lgkmcnt(1)
	v_add_u32_e32 v154, 0x124e0, v144
	ds_read_b128 v[154:157], v154
	v_lshlrev_b32_e32 v165, 16, v172
	v_and_b32_e32 v172, 0xffff0000, v172
	v_add_f32_e32 v132, v132, v172
	v_lshlrev_b32_e32 v172, 16, v173
	v_add_f32_e32 v133, v133, v172
	v_and_b32_e32 v172, 0xffff0000, v173
	v_add_f32_e32 v158, v158, v172
	v_lshlrev_b32_e32 v172, 16, v174
	v_add_f32_e32 v159, v159, v172
	v_and_b32_e32 v172, 0xffff0000, v174
	v_add_f32_e32 v160, v160, v172
	v_lshlrev_b32_e32 v172, 16, v175
	v_add_f32_e32 v161, v161, v172
	v_and_b32_e32 v172, 0xffff0000, v175
	v_add_f32_e32 v153, v153, v172
	v_add_f32_e32 v131, v131, v165
	s_waitcnt lgkmcnt(1)
	v_lshlrev_b32_e32 v165, 16, v168
	v_and_b32_e32 v168, 0xffff0000, v168
	v_add_f32_e32 v132, v132, v168
	v_lshlrev_b32_e32 v168, 16, v169
	v_add_f32_e32 v133, v133, v168
	v_and_b32_e32 v168, 0xffff0000, v169
	v_add_f32_e32 v158, v158, v168
	v_lshlrev_b32_e32 v168, 16, v170
	v_add_f32_e32 v159, v159, v168
	v_and_b32_e32 v168, 0xffff0000, v170
	v_add_f32_e32 v160, v160, v168
	v_lshlrev_b32_e32 v168, 16, v171
	v_add_f32_e32 v161, v161, v168
	v_and_b32_e32 v168, 0xffff0000, v171
	v_add_f32_e32 v153, v153, v168
	v_add_f32_e32 v131, v131, v165
	s_waitcnt lgkmcnt(0)
	v_lshlrev_b32_e32 v165, 16, v154
	v_add_f32_e32 v165, v131, v165
	v_and_b32_e32 v131, 0xffff0000, v154
	v_add_f32_e32 v154, v132, v131
	v_lshlrev_b32_e32 v131, 16, v155
	v_add_f32_e32 v166, v133, v131
	v_and_b32_e32 v131, 0xffff0000, v155
	v_add_f32_e32 v155, v158, v131
	v_lshlrev_b32_e32 v131, 16, v156
	v_add_f32_e32 v158, v159, v131
	v_and_b32_e32 v131, 0xffff0000, v156
	v_add_f32_e32 v156, v160, v131
	v_lshlrev_b32_e32 v131, 16, v157
	v_add_f32_e32 v159, v161, v131
	v_and_b32_e32 v131, 0xffff0000, v157
	v_add_f32_e32 v153, v153, v131
	ds_read_b128 v[130:133], v130
	s_waitcnt lgkmcnt(0)
	v_lshlrev_b32_e32 v157, 16, v130
	v_and_b32_e32 v130, 0xffff0000, v130
	v_add_f32_e32 v130, v154, v130
	v_lshlrev_b32_e32 v154, 16, v131
	v_and_b32_e32 v131, 0xffff0000, v131
	v_add_f32_e32 v157, v165, v157
	v_add_f32_e32 v131, v155, v131
	v_lshlrev_b32_e32 v155, 16, v132
	v_and_b32_e32 v132, 0xffff0000, v132
	v_add_f32_e32 v154, v166, v154
	v_add_f32_e32 v132, v156, v132
	v_lshlrev_b32_e32 v156, 16, v133
	v_and_b32_e32 v133, 0xffff0000, v133
	v_fma_f32 v145, v135, v157, -v145
	v_fma_f32 v130, v135, v130, -v146
	v_add_f32_e32 v155, v158, v155
	v_add_f32_e32 v133, v153, v133
	v_cvt_pk_bf16_f32 v130, v145, v130
	v_fma_f32 v145, v135, v154, -v147
	v_fma_f32 v131, v135, v131, -v148
	v_add_f32_e32 v156, v159, v156
	v_cvt_pk_bf16_f32 v131, v145, v131
	v_fma_f32 v145, v135, v155, -v149
	v_fma_f32 v132, v135, v132, -v150
	v_fma_f32 v133, v135, v133, -v152
	v_cvt_pk_bf16_f32 v132, v145, v132
	v_fma_f32 v145, v135, v156, -v151
	v_cvt_pk_bf16_f32 v133, v145, v133
	s_waitcnt vmcnt(15)
; __device__ __forceinline__ float bflo(unsigned u) { return __uint_as_float(u << 16); }
; __device__ __forceinline__ float bfhi(unsigned u) { return __uint_as_float(u & 0xffff0000u); }
; template <int W>
; __device__ __forceinline__ void pool_compute(const Params& p, int layer, int g, int dh, int tt, const int tidx) {
;     ...
;     for (int k4 = 0; k4 < 4; ++k4) {
;       const int ks = kb * 4 + k4;
;       float sum[8];
; #pragma unroll
;       for (int j = 0; j < 8; ++j) sum[j] = 0.f;
;       u32x4 x0 = *reinterpret_cast<const u32x4*>(xl + ks * 32);
; #pragma unroll
;       for (int i = 0; i < W; ++i) {
;         u32x4 xv = *reinterpret_cast<const u32x4*>(xl + ks * 32 - i * PXS);
;         sum[0] += bflo(xv.x); sum[1] += bfhi(xv.x); sum[2] += bflo(xv.y); sum[3] += bfhi(xv.y);
;         sum[4] += bflo(xv.z); sum[5] += bfhi(xv.z); sum[6] += bflo(xv.w); sum[7] += bfhi(xv.w);
;       }
;       u32x4 bfr;
;       bfr.x = pack2(sum[0] * inv - bflo(x0.x), sum[1] * inv - bfhi(x0.x));
;       bfr.y = pack2(sum[2] * inv - bflo(x0.y), sum[3] * inv - bfhi(x0.y));
;       bfr.z = pack2(sum[4] * inv - bflo(x0.z), sum[5] * inv - bfhi(x0.z));
;       bfr.w = pack2(sum[6] * inv - bflo(x0.w), sum[7] * inv - bfhi(x0.w));
; #pragma unroll
;       for (int d = 0; d < 4; ++d) acc[d] = __builtin_amdgcn_mfma_f32_32x32x16_bf16(as_bf16x8(av[k4][d]), as_bf16x8(bfr), acc[d], 0, 0, 0);
	v_mfma_f32_32x32x16_bf16 v[48:63], v[114:117], v[130:133], v[48:63]
	v_add_u32_e32 v114, 0x141e0, v144
	s_waitcnt vmcnt(13)
	v_mfma_f32_32x32x16_bf16 v[32:47], v[118:121], v[130:133], v[32:47]
	ds_read_b128 v[118:121], v114
	s_waitcnt vmcnt(11)
	v_mfma_f32_32x32x16_bf16 v[16:31], v[122:125], v[130:133], v[16:31]
	v_add_u32_e32 v122, 0x13fd0, v144
	ds_read_b128 v[122:125], v122
	s_waitcnt lgkmcnt(1)
	v_and_b32_e32 v115, 0xffff0000, v118
	v_lshlrev_b32_e32 v116, 16, v119
	v_and_b32_e32 v117, 0xffff0000, v119
	v_lshlrev_b32_e32 v114, 16, v118
	s_waitcnt lgkmcnt(0)
	v_lshlrev_b32_e32 v145, 16, v122
	s_waitcnt vmcnt(9)
	v_mfma_f32_32x32x16_bf16 v[0:15], v[126:129], v[130:133], v[0:15]
	v_add_f32_e32 v127, 0, v115
	v_and_b32_e32 v122, 0xffff0000, v122
	v_add_f32_e32 v128, 0, v116
	v_add_f32_e32 v127, v127, v122
	v_lshlrev_b32_e32 v122, 16, v123
	v_add_f32_e32 v129, 0, v117
	v_lshlrev_b32_e32 v118, 16, v120
	v_add_f32_e32 v128, v128, v122
	v_and_b32_e32 v122, 0xffff0000, v123
	v_add_f32_e32 v130, 0, v118
	v_and_b32_e32 v119, 0xffff0000, v120
	v_add_f32_e32 v129, v129, v122
	v_lshlrev_b32_e32 v122, 16, v124
	v_add_f32_e32 v131, 0, v119
	v_lshlrev_b32_e32 v120, 16, v121
	v_add_f32_e32 v130, v130, v122
	v_and_b32_e32 v122, 0xffff0000, v124
	v_add_f32_e32 v132, 0, v120
	v_and_b32_e32 v121, 0xffff0000, v121
	v_add_f32_e32 v131, v131, v122
	v_lshlrev_b32_e32 v122, 16, v125
	v_add_f32_e32 v133, 0, v121
	v_add_f32_e32 v132, v132, v122
	v_and_b32_e32 v122, 0xffff0000, v125
	v_add_f32_e32 v133, v133, v122
	v_add_u32_e32 v168, 0x13dc0, v144
	ds_read_b128 v[168:171], v168
	v_add_f32_e32 v126, 0, v114
	v_add_f32_e32 v126, v126, v145
	s_waitcnt lgkmcnt(0)
	v_add_u32_e32 v122, 0x13bb0, v144
	ds_read_b128 v[122:125], v122
	v_add_u32_e32 v172, 0x139a0, v144
	ds_read_b128 v[172:175], v172
	v_lshlrev_b32_e32 v145, 16, v168
	v_and_b32_e32 v168, 0xffff0000, v168
	v_add_f32_e32 v127, v127, v168
	v_lshlrev_b32_e32 v168, 16, v169
	v_add_f32_e32 v128, v128, v168
	v_and_b32_e32 v168, 0xffff0000, v169
	v_add_f32_e32 v129, v129, v168
	v_lshlrev_b32_e32 v168, 16, v170
	v_add_f32_e32 v130, v130, v168
	v_and_b32_e32 v168, 0xffff0000, v170
	v_add_f32_e32 v131, v131, v168
	v_lshlrev_b32_e32 v168, 16, v171
	v_add_f32_e32 v132, v132, v168
	v_and_b32_e32 v168, 0xffff0000, v171
	v_add_f32_e32 v133, v133, v168
	v_add_f32_e32 v126, v126, v145
	s_waitcnt lgkmcnt(1)
	v_add_u32_e32 v168, 0x13790, v144
	ds_read_b128 v[168:171], v168
	v_lshlrev_b32_e32 v145, 16, v122
	v_and_b32_e32 v122, 0xffff0000, v122
	v_add_f32_e32 v127, v127, v122
	v_lshlrev_b32_e32 v122, 16, v123
	v_add_f32_e32 v128, v128, v122
	v_and_b32_e32 v122, 0xffff0000, v123
	v_add_f32_e32 v129, v129, v122
	v_lshlrev_b32_e32 v122, 16, v124
	v_add_f32_e32 v130, v130, v122
	v_and_b32_e32 v122, 0xffff0000, v124
	v_add_f32_e32 v131, v131, v122
	v_lshlrev_b32_e32 v122, 16, v125
	v_add_f32_e32 v132, v132, v122
	v_and_b32_e32 v122, 0xffff0000, v125
	v_add_f32_e32 v133, v133, v122
	v_add_f32_e32 v126, v126, v145
	s_waitcnt lgkmcnt(1)
	v_add_u32_e32 v122, 0x13580, v144
	ds_read_b128 v[122:125], v122
	v_lshlrev_b32_e32 v145, 16, v172
	v_and_b32_e32 v172, 0xffff0000, v172
	v_add_f32_e32 v127, v127, v172
	v_lshlrev_b32_e32 v172, 16, v173
	v_add_f32_e32 v128, v128, v172
	v_and_b32_e32 v172, 0xffff0000, v173
	v_add_f32_e32 v129, v129, v172
	v_lshlrev_b32_e32 v172, 16, v174
	v_add_f32_e32 v130, v130, v172
	v_and_b32_e32 v172, 0xffff0000, v174
	v_add_f32_e32 v131, v131, v172
	v_lshlrev_b32_e32 v172, 16, v175
	v_add_f32_e32 v132, v132, v172
	v_and_b32_e32 v172, 0xffff0000, v175
	v_add_f32_e32 v133, v133, v172
	v_add_f32_e32 v126, v126, v145
	s_waitcnt lgkmcnt(1)
	v_add_u32_e32 v172, 0x13370, v144
	ds_read_b128 v[172:175], v172
	v_lshlrev_b32_e32 v145, 16, v168
	v_and_b32_e32 v168, 0xffff0000, v168
	v_add_f32_e32 v127, v127, v168
	v_lshlrev_b32_e32 v168, 16, v169
	v_add_f32_e32 v128, v128, v168
	v_and_b32_e32 v168, 0xffff0000, v169
	v_add_f32_e32 v129, v129, v168
	v_lshlrev_b32_e32 v168, 16, v170
	v_add_f32_e32 v130, v130, v168
	v_and_b32_e32 v168, 0xffff0000, v170
	v_add_f32_e32 v131, v131, v168
	v_lshlrev_b32_e32 v168, 16, v171
	v_add_f32_e32 v132, v132, v168
	v_and_b32_e32 v168, 0xffff0000, v171
	v_add_f32_e32 v133, v133, v168
	v_add_f32_e32 v126, v126, v145
	s_waitcnt lgkmcnt(1)
	v_add_u32_e32 v168, 0x13160, v144
	ds_read_b128 v[168:171], v168
	v_lshlrev_b32_e32 v145, 16, v122
	v_and_b32_e32 v122, 0xffff0000, v122
	v_add_f32_e32 v127, v127, v122
	v_lshlrev_b32_e32 v122, 16, v123
	v_add_f32_e32 v128, v128, v122
	v_and_b32_e32 v122, 0xffff0000, v123
	v_add_f32_e32 v129, v129, v122
	v_lshlrev_b32_e32 v122, 16, v124
	v_add_f32_e32 v130, v130, v122
	v_and_b32_e32 v122, 0xffff0000, v124
	v_add_f32_e32 v131, v131, v122
	v_lshlrev_b32_e32 v122, 16, v125
	v_add_f32_e32 v132, v132, v122
	v_and_b32_e32 v122, 0xffff0000, v125
	v_add_f32_e32 v133, v133, v122
	v_add_f32_e32 v126, v126, v145
	s_waitcnt lgkmcnt(1)
	v_add_u32_e32 v122, 0x12f50, v144
	ds_read_b128 v[122:125], v122
	v_lshlrev_b32_e32 v145, 16, v172
	v_and_b32_e32 v172, 0xffff0000, v172
	v_add_f32_e32 v127, v127, v172
	v_lshlrev_b32_e32 v172, 16, v173
	v_add_f32_e32 v128, v128, v172
	v_and_b32_e32 v172, 0xffff0000, v173
	v_add_f32_e32 v129, v129, v172
	v_lshlrev_b32_e32 v172, 16, v174
	v_add_f32_e32 v130, v130, v172
	v_and_b32_e32 v172, 0xffff0000, v174
	v_add_f32_e32 v131, v131, v172
	v_lshlrev_b32_e32 v172, 16, v175
	v_add_f32_e32 v132, v132, v172
	v_and_b32_e32 v172, 0xffff0000, v175
	v_add_f32_e32 v133, v133, v172
	v_add_f32_e32 v126, v126, v145
	s_waitcnt lgkmcnt(1)
; __device__ __forceinline__ float bflo(unsigned u) { return __uint_as_float(u << 16); }
; __device__ __forceinline__ float bfhi(unsigned u) { return __uint_as_float(u & 0xffff0000u); }
; template <int W>
; __device__ __forceinline__ void pool_compute(const Params& p, int layer, int g, int dh, int tt, const int tidx) {
;     ...
;     for (int k4 = 0; k4 < 4; ++k4) {
;       const int ks = kb * 4 + k4;
;       float sum[8];
; #pragma unroll
;       for (int j = 0; j < 8; ++j) sum[j] = 0.f;
;       u32x4 x0 = *reinterpret_cast<const u32x4*>(xl + ks * 32);
; #pragma unroll
;       for (int i = 0; i < W; ++i) {
;         u32x4 xv = *reinterpret_cast<const u32x4*>(xl + ks * 32 - i * PXS);
;         sum[0] += bflo(xv.x); sum[1] += bfhi(xv.x); sum[2] += bflo(xv.y); sum[3] += bfhi(xv.y);
;         sum[4] += bflo(xv.z); sum[5] += bfhi(xv.z); sum[6] += bflo(xv.w); sum[7] += bfhi(xv.w);
;       }
;       u32x4 bfr;
;       bfr.x = pack2(sum[0] * inv - bflo(x0.x), sum[1] * inv - bfhi(x0.x));
;       bfr.y = pack2(sum[2] * inv - bflo(x0.y), sum[3] * inv - bfhi(x0.y));
;       bfr.z = pack2(sum[4] * inv - bflo(x0.z), sum[5] * inv - bfhi(x0.z));
;       bfr.w = pack2(sum[6] * inv - bflo(x0.w), sum[7] * inv - bfhi(x0.w));
; #pragma unroll
;       for (int d = 0; d < 4; ++d) acc[d] = __builtin_amdgcn_mfma_f32_32x32x16_bf16(as_bf16x8(av[k4][d]), as_bf16x8(bfr), acc[d], 0, 0, 0);
	v_add_u32_e32 v172, 0x12d40, v144
	ds_read_b128 v[172:175], v172
	v_lshlrev_b32_e32 v145, 16, v168
	v_and_b32_e32 v168, 0xffff0000, v168
	v_add_f32_e32 v127, v127, v168
	v_lshlrev_b32_e32 v168, 16, v169
	v_add_f32_e32 v128, v128, v168
	v_and_b32_e32 v168, 0xffff0000, v169
	v_add_f32_e32 v129, v129, v168
	v_lshlrev_b32_e32 v168, 16, v170
	v_add_f32_e32 v130, v130, v168
	v_and_b32_e32 v168, 0xffff0000, v170
	v_add_f32_e32 v131, v131, v168
	v_lshlrev_b32_e32 v168, 16, v171
	v_add_f32_e32 v132, v132, v168
	v_and_b32_e32 v168, 0xffff0000, v171
	v_add_f32_e32 v133, v133, v168
	v_add_f32_e32 v126, v126, v145
	s_waitcnt lgkmcnt(1)
	v_add_u32_e32 v168, 0x12b30, v144
	ds_read_b128 v[168:171], v168
	v_lshlrev_b32_e32 v145, 16, v122
	v_and_b32_e32 v122, 0xffff0000, v122
	v_add_f32_e32 v127, v127, v122
	v_lshlrev_b32_e32 v122, 16, v123
	v_add_f32_e32 v128, v128, v122
	v_and_b32_e32 v122, 0xffff0000, v123
	v_add_f32_e32 v129, v129, v122
	v_lshlrev_b32_e32 v122, 16, v124
	v_add_f32_e32 v130, v130, v122
	v_and_b32_e32 v122, 0xffff0000, v124
	v_add_f32_e32 v131, v131, v122
	v_lshlrev_b32_e32 v122, 16, v125
	v_add_f32_e32 v132, v132, v122
	v_and_b32_e32 v122, 0xffff0000, v125
	v_add_f32_e32 v133, v133, v122
	v_add_f32_e32 v126, v126, v145
	s_waitcnt lgkmcnt(1)
	v_add_u32_e32 v122, 0x12920, v144
	ds_read_b128 v[122:125], v122
	v_lshlrev_b32_e32 v145, 16, v172
	v_and_b32_e32 v172, 0xffff0000, v172
	v_add_f32_e32 v127, v127, v172
	v_lshlrev_b32_e32 v172, 16, v173
	v_add_f32_e32 v128, v128, v172
	v_and_b32_e32 v172, 0xffff0000, v173
	v_add_f32_e32 v129, v129, v172
	v_lshlrev_b32_e32 v172, 16, v174
	v_add_f32_e32 v130, v130, v172
	v_and_b32_e32 v172, 0xffff0000, v174
	v_add_f32_e32 v131, v131, v172
	v_lshlrev_b32_e32 v172, 16, v175
	v_add_f32_e32 v132, v132, v172
	v_and_b32_e32 v172, 0xffff0000, v175
	v_add_f32_e32 v133, v133, v172
	v_add_f32_e32 v126, v126, v145
	s_waitcnt lgkmcnt(1)
	v_add_u32_e32 v172, 0x12710, v144
	ds_read_b128 v[172:175], v172
	v_lshlrev_b32_e32 v145, 16, v168
	v_and_b32_e32 v168, 0xffff0000, v168
	v_add_f32_e32 v127, v127, v168
	v_lshlrev_b32_e32 v168, 16, v169
	v_add_f32_e32 v128, v128, v168
	v_and_b32_e32 v168, 0xffff0000, v169
	v_add_f32_e32 v129, v129, v168
	v_lshlrev_b32_e32 v168, 16, v170
	v_add_f32_e32 v130, v130, v168
	v_and_b32_e32 v168, 0xffff0000, v170
	v_add_f32_e32 v131, v131, v168
	v_lshlrev_b32_e32 v168, 16, v171
	v_add_f32_e32 v132, v132, v168
	v_and_b32_e32 v168, 0xffff0000, v171
	v_add_f32_e32 v133, v133, v168
	v_add_f32_e32 v126, v126, v145
	s_waitcnt lgkmcnt(1)
	v_add_u32_e32 v168, 0x12500, v144
	ds_read_b128 v[168:171], v168
	v_lshlrev_b32_e32 v145, 16, v122
	v_and_b32_e32 v122, 0xffff0000, v122
	v_add_f32_e32 v127, v127, v122
	v_lshlrev_b32_e32 v122, 16, v123
	v_add_f32_e32 v128, v128, v122
	v_and_b32_e32 v122, 0xffff0000, v123
	v_add_f32_e32 v129, v129, v122
	v_lshlrev_b32_e32 v122, 16, v124
	v_add_f32_e32 v130, v130, v122
	v_and_b32_e32 v122, 0xffff0000, v124
	v_add_f32_e32 v131, v131, v122
	v_lshlrev_b32_e32 v122, 16, v125
	v_add_f32_e32 v132, v132, v122
	v_and_b32_e32 v122, 0xffff0000, v125
	v_add_f32_e32 v133, v133, v122
	v_add_f32_e32 v126, v126, v145
	s_waitcnt lgkmcnt(1)
	v_add_u32_e32 v122, 0x122f0, v144
	ds_read_b128 v[122:125], v122
	v_lshlrev_b32_e32 v145, 16, v172
	v_and_b32_e32 v172, 0xffff0000, v172
	v_add_f32_e32 v127, v127, v172
	v_lshlrev_b32_e32 v172, 16, v173
	v_add_f32_e32 v128, v128, v172
	v_and_b32_e32 v172, 0xffff0000, v173
	v_add_f32_e32 v129, v129, v172
	v_lshlrev_b32_e32 v172, 16, v174
	v_add_f32_e32 v130, v130, v172
	v_and_b32_e32 v172, 0xffff0000, v174
	v_add_f32_e32 v131, v131, v172
	v_lshlrev_b32_e32 v172, 16, v175
	v_add_f32_e32 v132, v132, v172
	v_and_b32_e32 v172, 0xffff0000, v175
	v_add_f32_e32 v133, v133, v172
	v_add_f32_e32 v126, v126, v145
	s_waitcnt lgkmcnt(1)
	v_lshlrev_b32_e32 v145, 16, v168
	v_and_b32_e32 v168, 0xffff0000, v168
	v_add_f32_e32 v127, v127, v168
	v_lshlrev_b32_e32 v168, 16, v169
	v_add_f32_e32 v128, v128, v168
	v_and_b32_e32 v168, 0xffff0000, v169
	v_add_f32_e32 v129, v129, v168
	v_lshlrev_b32_e32 v168, 16, v170
	v_add_f32_e32 v130, v130, v168
	v_and_b32_e32 v168, 0xffff0000, v170
	v_add_f32_e32 v131, v131, v168
	v_lshlrev_b32_e32 v168, 16, v171
	v_add_f32_e32 v132, v132, v168
	v_and_b32_e32 v168, 0xffff0000, v171
	v_add_f32_e32 v133, v133, v168
	v_add_f32_e32 v126, v126, v145
	s_waitcnt lgkmcnt(0)
	v_lshlrev_b32_e32 v145, 16, v122
	v_and_b32_e32 v122, 0xffff0000, v122
	v_add_f32_e32 v126, v126, v145
	v_add_f32_e32 v122, v127, v122
	v_lshlrev_b32_e32 v127, 16, v123
	v_and_b32_e32 v123, 0xffff0000, v123
	v_add_f32_e32 v127, v128, v127
	v_add_f32_e32 v123, v129, v123
	v_lshlrev_b32_e32 v128, 16, v124
	v_and_b32_e32 v124, 0xffff0000, v124
	v_fma_f32 v114, v135, v126, -v114
	v_fma_f32 v115, v135, v122, -v115
	v_add_f32_e32 v128, v130, v128
	v_add_f32_e32 v124, v131, v124
	v_lshlrev_b32_e32 v129, 16, v125
	v_cvt_pk_bf16_f32 v114, v114, v115
	v_fma_f32 v115, v135, v127, -v116
	v_fma_f32 v116, v135, v123, -v117
	v_add_f32_e32 v129, v132, v129
	v_and_b32_e32 v125, 0xffff0000, v125
	v_cvt_pk_bf16_f32 v115, v115, v116
	v_fma_f32 v116, v135, v128, -v118
	v_fma_f32 v117, v135, v124, -v119
	v_add_f32_e32 v125, v133, v125
	v_cvt_pk_bf16_f32 v116, v116, v117
	v_fma_f32 v117, v135, v129, -v120
	v_fma_f32 v118, v135, v125, -v121
	v_cvt_pk_bf16_f32 v117, v117, v118
	s_nop 0
	v_mfma_f32_32x32x16_bf16 v[48:63], v[98:101], v[114:117], v[48:63]
	v_add_u32_e32 v98, 0x14200, v144
	v_mfma_f32_32x32x16_bf16 v[32:47], v[102:105], v[114:117], v[32:47]
	ds_read_b128 v[102:105], v98
	v_mfma_f32_32x32x16_bf16 v[16:31], v[106:109], v[114:117], v[16:31]
	v_add_u32_e32 v106, 0x13ff0, v144
	ds_read_b128 v[106:109], v106
	s_waitcnt lgkmcnt(1)
; __device__ __forceinline__ float bflo(unsigned u) { return __uint_as_float(u << 16); }
; __device__ __forceinline__ float bfhi(unsigned u) { return __uint_as_float(u & 0xffff0000u); }
; template <int W>
; __device__ __forceinline__ void pool_compute(const Params& p, int layer, int g, int dh, int tt, const int tidx) {
;     ...
;     for (int k4 = 0; k4 < 4; ++k4) {
;       const int ks = kb * 4 + k4;
;       float sum[8];
; #pragma unroll
;       for (int j = 0; j < 8; ++j) sum[j] = 0.f;
;       u32x4 x0 = *reinterpret_cast<const u32x4*>(xl + ks * 32);
; #pragma unroll
;       for (int i = 0; i < W; ++i) {
;         u32x4 xv = *reinterpret_cast<const u32x4*>(xl + ks * 32 - i * PXS);
;         sum[0] += bflo(xv.x); sum[1] += bfhi(xv.x); sum[2] += bflo(xv.y); sum[3] += bfhi(xv.y);
;         sum[4] += bflo(xv.z); sum[5] += bfhi(xv.z); sum[6] += bflo(xv.w); sum[7] += bfhi(xv.w);
;       }
;       u32x4 bfr;
;       bfr.x = pack2(sum[0] * inv - bflo(x0.x), sum[1] * inv - bfhi(x0.x));
;       bfr.y = pack2(sum[2] * inv - bflo(x0.y), sum[3] * inv - bfhi(x0.y));
;       bfr.z = pack2(sum[4] * inv - bflo(x0.z), sum[5] * inv - bfhi(x0.z));
;       bfr.w = pack2(sum[6] * inv - bflo(x0.w), sum[7] * inv - bfhi(x0.w));
; #pragma unroll
;       for (int d = 0; d < 4; ++d) acc[d] = __builtin_amdgcn_mfma_f32_32x32x16_bf16(as_bf16x8(av[k4][d]), as_bf16x8(bfr), acc[d], 0, 0, 0);
	v_and_b32_e32 v99, 0xffff0000, v102
	v_lshlrev_b32_e32 v100, 16, v103
	v_and_b32_e32 v101, 0xffff0000, v103
	v_lshlrev_b32_e32 v98, 16, v102
	s_waitcnt lgkmcnt(0)
	v_lshlrev_b32_e32 v118, 16, v106
	s_waitcnt vmcnt(8)
	v_mfma_f32_32x32x16_bf16 v[0:15], v[110:113], v[114:117], v[0:15]
	v_add_f32_e32 v111, 0, v99
	v_and_b32_e32 v106, 0xffff0000, v106
	v_add_f32_e32 v112, 0, v100
	v_add_f32_e32 v111, v111, v106
	v_lshlrev_b32_e32 v106, 16, v107
	v_add_f32_e32 v113, 0, v101
	v_lshlrev_b32_e32 v102, 16, v104
	v_add_f32_e32 v112, v112, v106
	v_and_b32_e32 v106, 0xffff0000, v107
	v_add_f32_e32 v114, 0, v102
	v_and_b32_e32 v103, 0xffff0000, v104
	v_add_f32_e32 v113, v113, v106
	v_lshlrev_b32_e32 v106, 16, v108
	v_add_f32_e32 v115, 0, v103
	v_lshlrev_b32_e32 v104, 16, v105
	v_add_f32_e32 v114, v114, v106
	v_and_b32_e32 v106, 0xffff0000, v108
	v_add_f32_e32 v116, 0, v104
	v_and_b32_e32 v105, 0xffff0000, v105
	v_add_f32_e32 v115, v115, v106
	v_lshlrev_b32_e32 v106, 16, v109
	v_add_f32_e32 v117, 0, v105
	v_add_f32_e32 v116, v116, v106
	v_and_b32_e32 v106, 0xffff0000, v109
	v_add_f32_e32 v117, v117, v106
	v_add_u32_e32 v168, 0x13de0, v144
	ds_read_b128 v[168:171], v168
	v_add_f32_e32 v110, 0, v98
	v_add_f32_e32 v110, v110, v118
	s_waitcnt lgkmcnt(0)
	v_add_u32_e32 v106, 0x13bd0, v144
	ds_read_b128 v[106:109], v106
	v_add_u32_e32 v172, 0x139c0, v144
	ds_read_b128 v[172:175], v172
	v_lshlrev_b32_e32 v118, 16, v168
	v_and_b32_e32 v168, 0xffff0000, v168
	v_add_f32_e32 v111, v111, v168
	v_lshlrev_b32_e32 v168, 16, v169
	v_add_f32_e32 v112, v112, v168
	v_and_b32_e32 v168, 0xffff0000, v169
	v_add_f32_e32 v113, v113, v168
	v_lshlrev_b32_e32 v168, 16, v170
	v_add_f32_e32 v114, v114, v168
	v_and_b32_e32 v168, 0xffff0000, v170
	v_add_f32_e32 v115, v115, v168
	v_lshlrev_b32_e32 v168, 16, v171
	v_add_f32_e32 v116, v116, v168
	v_and_b32_e32 v168, 0xffff0000, v171
	v_add_f32_e32 v117, v117, v168
	v_add_f32_e32 v110, v110, v118
	s_waitcnt lgkmcnt(1)
	v_add_u32_e32 v168, 0x137b0, v144
	ds_read_b128 v[168:171], v168
	v_lshlrev_b32_e32 v118, 16, v106
	v_and_b32_e32 v106, 0xffff0000, v106
	v_add_f32_e32 v111, v111, v106
	v_lshlrev_b32_e32 v106, 16, v107
	v_add_f32_e32 v112, v112, v106
	v_and_b32_e32 v106, 0xffff0000, v107
	v_add_f32_e32 v113, v113, v106
	v_lshlrev_b32_e32 v106, 16, v108
	v_add_f32_e32 v114, v114, v106
	v_and_b32_e32 v106, 0xffff0000, v108
	v_add_f32_e32 v115, v115, v106
	v_lshlrev_b32_e32 v106, 16, v109
	v_add_f32_e32 v116, v116, v106
	v_and_b32_e32 v106, 0xffff0000, v109
	v_add_f32_e32 v117, v117, v106
	v_add_f32_e32 v110, v110, v118
	s_waitcnt lgkmcnt(1)
	v_add_u32_e32 v106, 0x135a0, v144
	ds_read_b128 v[106:109], v106
	v_lshlrev_b32_e32 v118, 16, v172
	v_and_b32_e32 v172, 0xffff0000, v172
	v_add_f32_e32 v111, v111, v172
	v_lshlrev_b32_e32 v172, 16, v173
	v_add_f32_e32 v112, v112, v172
	v_and_b32_e32 v172, 0xffff0000, v173
	v_add_f32_e32 v113, v113, v172
	v_lshlrev_b32_e32 v172, 16, v174
	v_add_f32_e32 v114, v114, v172
	v_and_b32_e32 v172, 0xffff0000, v174
	v_add_f32_e32 v115, v115, v172
	v_lshlrev_b32_e32 v172, 16, v175
	v_add_f32_e32 v116, v116, v172
	v_and_b32_e32 v172, 0xffff0000, v175
	v_add_f32_e32 v117, v117, v172
	v_add_f32_e32 v110, v110, v118
	s_waitcnt lgkmcnt(1)
	v_lshlrev_b32_e32 v118, 16, v168
	v_and_b32_e32 v168, 0xffff0000, v168
	v_add_f32_e32 v111, v111, v168
	v_lshlrev_b32_e32 v168, 16, v169
	v_add_f32_e32 v112, v112, v168
	v_and_b32_e32 v168, 0xffff0000, v169
	v_add_f32_e32 v113, v113, v168
	v_lshlrev_b32_e32 v168, 16, v170
	v_add_f32_e32 v114, v114, v168
	v_and_b32_e32 v168, 0xffff0000, v170
	v_add_f32_e32 v115, v115, v168
	v_lshlrev_b32_e32 v168, 16, v171
	v_add_f32_e32 v116, v116, v168
	v_and_b32_e32 v168, 0xffff0000, v171
	v_add_f32_e32 v117, v117, v168
	v_add_f32_e32 v110, v110, v118
	s_waitcnt lgkmcnt(0)
	v_lshlrev_b32_e32 v118, 16, v106
	v_and_b32_e32 v106, 0xffff0000, v106
	v_add_f32_e32 v119, v111, v106
	v_lshlrev_b32_e32 v106, 16, v107
	v_add_f32_e32 v120, v112, v106
	v_and_b32_e32 v106, 0xffff0000, v107
	v_add_f32_e32 v121, v113, v106
	v_lshlrev_b32_e32 v106, 16, v108
	v_add_f32_e32 v114, v114, v106
	v_and_b32_e32 v106, 0xffff0000, v108
	v_add_f32_e32 v115, v115, v106
	v_lshlrev_b32_e32 v106, 16, v109
	v_add_f32_e32 v116, v116, v106
	v_and_b32_e32 v106, 0xffff0000, v109
	v_add_f32_e32 v117, v117, v106
	v_add_u32_e32 v106, 0x13390, v144
	v_add_f32_e32 v118, v110, v118
	ds_read_b128 v[110:113], v106
	s_waitcnt lgkmcnt(0)
	v_lshlrev_b32_e32 v106, 16, v110
	v_and_b32_e32 v107, 0xffff0000, v110
	v_lshlrev_b32_e32 v110, 16, v112
	v_lshlrev_b32_e32 v108, 16, v111
	v_and_b32_e32 v109, 0xffff0000, v111
	v_add_f32_e32 v110, v114, v110
	v_and_b32_e32 v111, 0xffff0000, v112
	v_lshlrev_b32_e32 v112, 16, v113
	v_and_b32_e32 v113, 0xffff0000, v113
	v_add_u32_e32 v114, 0x13180, v144
	v_add_f32_e32 v111, v115, v111
	v_add_f32_e32 v112, v116, v112
	v_add_f32_e32 v113, v117, v113
	ds_read_b128 v[114:117], v114
	v_add_f32_e32 v106, v118, v106
	v_add_f32_e32 v107, v119, v107
	v_add_f32_e32 v108, v120, v108
	v_add_f32_e32 v109, v121, v109
	s_waitcnt lgkmcnt(0)
	v_lshlrev_b32_e32 v118, 16, v114
	v_add_f32_e32 v118, v106, v118
	v_and_b32_e32 v106, 0xffff0000, v114
	v_add_f32_e32 v114, v107, v106
	v_lshlrev_b32_e32 v106, 16, v115
	v_add_f32_e32 v119, v108, v106
	v_and_b32_e32 v106, 0xffff0000, v115
	v_add_f32_e32 v115, v109, v106
	v_lshlrev_b32_e32 v106, 16, v116
	v_add_f32_e32 v110, v110, v106
	v_and_b32_e32 v106, 0xffff0000, v116
	v_add_f32_e32 v111, v111, v106
	v_lshlrev_b32_e32 v106, 16, v117
	v_add_f32_e32 v112, v112, v106
	v_and_b32_e32 v106, 0xffff0000, v117
	v_add_f32_e32 v113, v113, v106
	v_add_u32_e32 v106, 0x12f70, v144
	ds_read_b128 v[106:109], v106
	s_waitcnt lgkmcnt(0)
; __device__ __forceinline__ float bflo(unsigned u) { return __uint_as_float(u << 16); }
; __device__ __forceinline__ float bfhi(unsigned u) { return __uint_as_float(u & 0xffff0000u); }
; template <int W>
; __device__ __forceinline__ void pool_compute(const Params& p, int layer, int g, int dh, int tt, const int tidx) {
;     ...
;     for (int k4 = 0; k4 < 4; ++k4) {
;       const int ks = kb * 4 + k4;
;       float sum[8];
; #pragma unroll
;       for (int j = 0; j < 8; ++j) sum[j] = 0.f;
;       u32x4 x0 = *reinterpret_cast<const u32x4*>(xl + ks * 32);
; #pragma unroll
;       for (int i = 0; i < W; ++i) {
;         u32x4 xv = *reinterpret_cast<const u32x4*>(xl + ks * 32 - i * PXS);
;         sum[0] += bflo(xv.x); sum[1] += bfhi(xv.x); sum[2] += bflo(xv.y); sum[3] += bfhi(xv.y);
;         sum[4] += bflo(xv.z); sum[5] += bfhi(xv.z); sum[6] += bflo(xv.w); sum[7] += bfhi(xv.w);
;       }
;       u32x4 bfr;
;       bfr.x = pack2(sum[0] * inv - bflo(x0.x), sum[1] * inv - bfhi(x0.x));
;       bfr.y = pack2(sum[2] * inv - bflo(x0.y), sum[3] * inv - bfhi(x0.y));
;       bfr.z = pack2(sum[4] * inv - bflo(x0.z), sum[5] * inv - bfhi(x0.z));
;       bfr.w = pack2(sum[6] * inv - bflo(x0.w), sum[7] * inv - bfhi(x0.w));
; #pragma unroll
;       for (int d = 0; d < 4; ++d) acc[d] = __builtin_amdgcn_mfma_f32_32x32x16_bf16(as_bf16x8(av[k4][d]), as_bf16x8(bfr), acc[d], 0, 0, 0);
	v_add_u32_e32 v172, 0x12d60, v144
	ds_read_b128 v[172:175], v172
	v_add_u32_e32 v168, 0x12b50, v144
	ds_read_b128 v[168:171], v168
	v_lshlrev_b32_e32 v116, 16, v106
	v_and_b32_e32 v106, 0xffff0000, v106
	v_add_f32_e32 v114, v114, v106
	v_lshlrev_b32_e32 v106, 16, v107
	v_add_f32_e32 v117, v119, v106
	v_and_b32_e32 v106, 0xffff0000, v107
	v_add_f32_e32 v115, v115, v106
	v_lshlrev_b32_e32 v106, 16, v108
	v_add_f32_e32 v110, v110, v106
	v_and_b32_e32 v106, 0xffff0000, v108
	v_add_f32_e32 v111, v111, v106
	v_lshlrev_b32_e32 v106, 16, v109
	v_add_f32_e32 v112, v112, v106
	v_and_b32_e32 v106, 0xffff0000, v109
	v_add_f32_e32 v113, v113, v106
	v_add_f32_e32 v116, v118, v116
	s_waitcnt lgkmcnt(1)
	v_add_u32_e32 v106, 0x12940, v144
	ds_read_b128 v[106:109], v106
	v_lshlrev_b32_e32 v118, 16, v172
	v_and_b32_e32 v172, 0xffff0000, v172
	v_add_f32_e32 v114, v114, v172
	v_lshlrev_b32_e32 v172, 16, v173
	v_add_f32_e32 v117, v117, v172
	v_and_b32_e32 v172, 0xffff0000, v173
	v_add_f32_e32 v115, v115, v172
	v_lshlrev_b32_e32 v172, 16, v174
	v_add_f32_e32 v110, v110, v172
	v_and_b32_e32 v172, 0xffff0000, v174
	v_add_f32_e32 v111, v111, v172
	v_lshlrev_b32_e32 v172, 16, v175
	v_add_f32_e32 v112, v112, v172
	v_and_b32_e32 v172, 0xffff0000, v175
	v_add_f32_e32 v113, v113, v172
	v_add_f32_e32 v116, v116, v118
	s_waitcnt lgkmcnt(1)
	v_add_u32_e32 v172, 0x12730, v144
	ds_read_b128 v[172:175], v172
	v_lshlrev_b32_e32 v118, 16, v168
	v_and_b32_e32 v168, 0xffff0000, v168
	v_add_f32_e32 v114, v114, v168
	v_lshlrev_b32_e32 v168, 16, v169
	v_add_f32_e32 v117, v117, v168
	v_and_b32_e32 v168, 0xffff0000, v169
	v_add_f32_e32 v115, v115, v168
	v_lshlrev_b32_e32 v168, 16, v170
	v_add_f32_e32 v110, v110, v168
	v_and_b32_e32 v168, 0xffff0000, v170
	v_add_f32_e32 v111, v111, v168
	v_lshlrev_b32_e32 v168, 16, v171
	v_add_f32_e32 v112, v112, v168
	v_and_b32_e32 v168, 0xffff0000, v171
	v_add_f32_e32 v113, v113, v168
	v_add_f32_e32 v116, v116, v118
	s_waitcnt lgkmcnt(1)
	v_add_u32_e32 v168, 0x12520, v144
	ds_read_b128 v[168:171], v168
	v_lshlrev_b32_e32 v118, 16, v106
	v_and_b32_e32 v106, 0xffff0000, v106
	v_add_f32_e32 v114, v114, v106
	v_lshlrev_b32_e32 v106, 16, v107
	v_add_f32_e32 v117, v117, v106
	v_and_b32_e32 v106, 0xffff0000, v107
	v_add_f32_e32 v115, v115, v106
	v_lshlrev_b32_e32 v106, 16, v108
	v_add_f32_e32 v110, v110, v106
	v_and_b32_e32 v106, 0xffff0000, v108
	v_add_f32_e32 v111, v111, v106
	v_lshlrev_b32_e32 v106, 16, v109
	v_add_f32_e32 v112, v112, v106
	v_and_b32_e32 v106, 0xffff0000, v109
	v_add_f32_e32 v113, v113, v106
	v_add_f32_e32 v116, v116, v118
	s_waitcnt lgkmcnt(1)
	v_add_u32_e32 v106, 0x12310, v144
	ds_read_b128 v[106:109], v106
	v_lshlrev_b32_e32 v118, 16, v172
	v_and_b32_e32 v172, 0xffff0000, v172
	v_add_f32_e32 v114, v114, v172
	v_lshlrev_b32_e32 v172, 16, v173
	v_add_f32_e32 v117, v117, v172
	v_and_b32_e32 v172, 0xffff0000, v173
	v_add_f32_e32 v115, v115, v172
	v_lshlrev_b32_e32 v172, 16, v174
	v_add_f32_e32 v110, v110, v172
	v_and_b32_e32 v172, 0xffff0000, v174
	v_add_f32_e32 v111, v111, v172
	v_lshlrev_b32_e32 v172, 16, v175
	v_add_f32_e32 v112, v112, v172
	v_and_b32_e32 v172, 0xffff0000, v175
	v_add_f32_e32 v113, v113, v172
	v_add_f32_e32 v116, v116, v118
	s_waitcnt lgkmcnt(1)
	v_lshlrev_b32_e32 v118, 16, v168
	v_and_b32_e32 v168, 0xffff0000, v168
	v_add_f32_e32 v114, v114, v168
	v_lshlrev_b32_e32 v168, 16, v169
	v_add_f32_e32 v117, v117, v168
	v_and_b32_e32 v168, 0xffff0000, v169
	v_add_f32_e32 v115, v115, v168
	v_lshlrev_b32_e32 v168, 16, v170
	v_add_f32_e32 v110, v110, v168
	v_and_b32_e32 v168, 0xffff0000, v170
	v_add_f32_e32 v111, v111, v168
	v_lshlrev_b32_e32 v168, 16, v171
	v_add_f32_e32 v112, v112, v168
	v_and_b32_e32 v168, 0xffff0000, v171
	v_add_f32_e32 v113, v113, v168
	v_add_f32_e32 v116, v116, v118
	s_waitcnt lgkmcnt(0)
	v_lshlrev_b32_e32 v118, 16, v106
	v_and_b32_e32 v106, 0xffff0000, v106
	v_add_f32_e32 v116, v116, v118
	v_add_f32_e32 v106, v114, v106
	v_lshlrev_b32_e32 v114, 16, v107
	v_and_b32_e32 v107, 0xffff0000, v107
	v_add_f32_e32 v114, v117, v114
	v_add_f32_e32 v107, v115, v107
	v_lshlrev_b32_e32 v115, 16, v108
	v_and_b32_e32 v108, 0xffff0000, v108
	v_fma_f32 v98, v135, v116, -v98
	v_fma_f32 v99, v135, v106, -v99
	v_add_f32_e32 v110, v110, v115
	v_add_f32_e32 v108, v111, v108
	v_lshlrev_b32_e32 v111, 16, v109
	v_cvt_pk_bf16_f32 v98, v98, v99
	v_fma_f32 v99, v135, v114, -v100
	v_fma_f32 v100, v135, v107, -v101
	v_add_f32_e32 v111, v112, v111
	v_and_b32_e32 v109, 0xffff0000, v109
	v_cvt_pk_bf16_f32 v99, v99, v100
	v_fma_f32 v100, v135, v110, -v102
	v_fma_f32 v101, v135, v108, -v103
	v_add_f32_e32 v109, v113, v109
	v_cvt_pk_bf16_f32 v100, v100, v101
	v_fma_f32 v101, v135, v111, -v104
	v_fma_f32 v102, v135, v109, -v105
	v_cvt_pk_bf16_f32 v101, v101, v102
	s_waitcnt vmcnt(7)
	v_mfma_f32_32x32x16_bf16 v[48:63], v[80:83], v[98:101], v[48:63]
	v_add_u32_e32 v80, 0x14220, v144
	s_waitcnt vmcnt(3)
	v_mfma_f32_32x32x16_bf16 v[16:31], v[88:91], v[98:101], v[16:31]
	ds_read_b128 v[88:91], v80
	s_waitcnt lgkmcnt(0)
	v_lshlrev_b32_e32 v83, 16, v90
	v_and_b32_e32 v82, 0xffff0000, v90
	v_mfma_f32_32x32x16_bf16 v[32:47], v[84:87], v[98:101], v[32:47]
	v_lshlrev_b32_e32 v86, 16, v88
	v_and_b32_e32 v87, 0xffff0000, v88
	v_add_u32_e32 v88, 0x14010, v144
	v_lshlrev_b32_e32 v84, 16, v89
	v_and_b32_e32 v85, 0xffff0000, v89
	v_lshlrev_b32_e32 v80, 16, v91
	v_and_b32_e32 v81, 0xffff0000, v91
	ds_read_b128 v[88:91], v88
	s_waitcnt vmcnt(1)
	v_mfma_f32_32x32x16_bf16 v[0:15], v[92:95], v[98:101], v[0:15]
	v_add_f32_e32 v93, 0, v87
	v_add_f32_e32 v94, 0, v84
	v_add_f32_e32 v95, 0, v85
	s_waitcnt lgkmcnt(0)
; __device__ __forceinline__ float bflo(unsigned u) { return __uint_as_float(u << 16); }
; __device__ __forceinline__ float bfhi(unsigned u) { return __uint_as_float(u & 0xffff0000u); }
; template <int W>
; __device__ __forceinline__ void pool_compute(const Params& p, int layer, int g, int dh, int tt, const int tidx) {
;     ...
;       u32x4 x0 = *reinterpret_cast<const u32x4*>(xl + ks * 32);
; #pragma unroll
;       for (int i = 0; i < W; ++i) {
;         u32x4 xv = *reinterpret_cast<const u32x4*>(xl + ks * 32 - i * PXS);
;         sum[0] += bflo(xv.x); sum[1] += bfhi(xv.x); sum[2] += bflo(xv.y); sum[3] += bfhi(xv.y);
;         sum[4] += bflo(xv.z); sum[5] += bfhi(xv.z); sum[6] += bflo(xv.w); sum[7] += bfhi(xv.w);
;       }
	v_lshlrev_b32_e32 v102, 16, v88
	v_and_b32_e32 v88, 0xffff0000, v88
	v_add_f32_e32 v93, v93, v88
	v_lshlrev_b32_e32 v88, 16, v89
	v_add_f32_e32 v94, v94, v88
	v_and_b32_e32 v88, 0xffff0000, v89
	v_add_f32_e32 v98, 0, v83
	v_add_f32_e32 v95, v95, v88
	v_lshlrev_b32_e32 v88, 16, v90
	v_add_f32_e32 v99, 0, v82
	v_add_f32_e32 v98, v98, v88
	v_and_b32_e32 v88, 0xffff0000, v90
	v_add_f32_e32 v100, 0, v80
	v_add_f32_e32 v99, v99, v88
	v_lshlrev_b32_e32 v88, 16, v91
	v_add_f32_e32 v101, 0, v81
	v_add_f32_e32 v100, v100, v88
	v_and_b32_e32 v88, 0xffff0000, v91
	v_add_f32_e32 v101, v101, v88
	v_add_u32_e32 v168, 0x13e00, v144
	ds_read_b128 v[168:171], v168
	v_add_f32_e32 v92, 0, v86
	v_add_f32_e32 v92, v92, v102
	s_waitcnt lgkmcnt(0)
	v_add_u32_e32 v88, 0x13bf0, v144
	ds_read_b128 v[88:91], v88
	v_add_u32_e32 v172, 0x139e0, v144
	ds_read_b128 v[172:175], v172
	v_lshlrev_b32_e32 v102, 16, v168
	v_and_b32_e32 v168, 0xffff0000, v168
	v_add_f32_e32 v93, v93, v168
	v_lshlrev_b32_e32 v168, 16, v169
	v_add_f32_e32 v94, v94, v168
	v_and_b32_e32 v168, 0xffff0000, v169
	v_add_f32_e32 v95, v95, v168
	v_lshlrev_b32_e32 v168, 16, v170
	v_add_f32_e32 v98, v98, v168
	v_and_b32_e32 v168, 0xffff0000, v170
	v_add_f32_e32 v99, v99, v168
	v_lshlrev_b32_e32 v168, 16, v171
	v_add_f32_e32 v100, v100, v168
	v_and_b32_e32 v168, 0xffff0000, v171
	v_add_f32_e32 v101, v101, v168
	v_add_f32_e32 v92, v92, v102
	s_waitcnt lgkmcnt(1)
	v_add_u32_e32 v168, 0x137d0, v144
	ds_read_b128 v[168:171], v168
	v_lshlrev_b32_e32 v102, 16, v88
	v_and_b32_e32 v88, 0xffff0000, v88
	v_add_f32_e32 v93, v93, v88
	v_lshlrev_b32_e32 v88, 16, v89
	v_add_f32_e32 v94, v94, v88
	v_and_b32_e32 v88, 0xffff0000, v89
	v_add_f32_e32 v95, v95, v88
	v_lshlrev_b32_e32 v88, 16, v90
	v_add_f32_e32 v98, v98, v88
	v_and_b32_e32 v88, 0xffff0000, v90
	v_add_f32_e32 v99, v99, v88
	v_lshlrev_b32_e32 v88, 16, v91
	v_add_f32_e32 v100, v100, v88
	v_and_b32_e32 v88, 0xffff0000, v91
	v_add_f32_e32 v101, v101, v88
	v_add_f32_e32 v92, v92, v102
	s_waitcnt lgkmcnt(1)
	v_add_u32_e32 v88, 0x135c0, v144
	ds_read_b128 v[88:91], v88
	v_lshlrev_b32_e32 v102, 16, v172
	v_and_b32_e32 v172, 0xffff0000, v172
	v_add_f32_e32 v93, v93, v172
	v_lshlrev_b32_e32 v172, 16, v173
	v_add_f32_e32 v94, v94, v172
	v_and_b32_e32 v172, 0xffff0000, v173
	v_add_f32_e32 v95, v95, v172
	v_lshlrev_b32_e32 v172, 16, v174
	v_add_f32_e32 v98, v98, v172
	v_and_b32_e32 v172, 0xffff0000, v174
	v_add_f32_e32 v99, v99, v172
	v_lshlrev_b32_e32 v172, 16, v175
	v_add_f32_e32 v100, v100, v172
	v_and_b32_e32 v172, 0xffff0000, v175
	v_add_f32_e32 v101, v101, v172
	v_add_f32_e32 v92, v92, v102
	s_waitcnt lgkmcnt(1)
	v_lshlrev_b32_e32 v102, 16, v168
	v_and_b32_e32 v168, 0xffff0000, v168
	v_add_f32_e32 v93, v93, v168
	v_lshlrev_b32_e32 v168, 16, v169
	v_add_f32_e32 v94, v94, v168
	v_and_b32_e32 v168, 0xffff0000, v169
	v_add_f32_e32 v95, v95, v168
	v_lshlrev_b32_e32 v168, 16, v170
	v_add_f32_e32 v98, v98, v168
	v_and_b32_e32 v168, 0xffff0000, v170
	v_add_f32_e32 v99, v99, v168
	v_lshlrev_b32_e32 v168, 16, v171
	v_add_f32_e32 v100, v100, v168
	v_and_b32_e32 v168, 0xffff0000, v171
	v_add_f32_e32 v101, v101, v168
	v_add_f32_e32 v92, v92, v102
	s_waitcnt lgkmcnt(0)
	v_lshlrev_b32_e32 v102, 16, v88
	v_and_b32_e32 v88, 0xffff0000, v88
	v_add_f32_e32 v103, v93, v88
	v_lshlrev_b32_e32 v88, 16, v89
	v_add_f32_e32 v104, v94, v88
	v_and_b32_e32 v88, 0xffff0000, v89
	v_add_f32_e32 v105, v95, v88
	v_lshlrev_b32_e32 v88, 16, v90
	v_add_f32_e32 v98, v98, v88
	v_and_b32_e32 v88, 0xffff0000, v90
	v_add_f32_e32 v99, v99, v88
	v_lshlrev_b32_e32 v88, 16, v91
	v_add_f32_e32 v100, v100, v88
	v_and_b32_e32 v88, 0xffff0000, v91
	v_add_f32_e32 v101, v101, v88
	v_add_u32_e32 v88, 0x133b0, v144
	v_add_f32_e32 v102, v92, v102
	ds_read_b128 v[92:95], v88
	s_waitcnt lgkmcnt(0)
	v_lshlrev_b32_e32 v88, 16, v92
	v_and_b32_e32 v89, 0xffff0000, v92
	v_lshlrev_b32_e32 v92, 16, v94
	v_lshlrev_b32_e32 v90, 16, v93
	v_and_b32_e32 v91, 0xffff0000, v93
	v_add_f32_e32 v92, v98, v92
	v_and_b32_e32 v93, 0xffff0000, v94
	v_lshlrev_b32_e32 v94, 16, v95
	v_and_b32_e32 v95, 0xffff0000, v95
	v_add_u32_e32 v98, 0x131a0, v144
	v_add_f32_e32 v93, v99, v93
	v_add_f32_e32 v94, v100, v94
	v_add_f32_e32 v95, v101, v95
	ds_read_b128 v[98:101], v98
	v_add_f32_e32 v88, v102, v88
	v_add_f32_e32 v89, v103, v89
	v_add_f32_e32 v90, v104, v90
	v_add_f32_e32 v91, v105, v91
	s_waitcnt lgkmcnt(0)
	v_lshlrev_b32_e32 v102, 16, v98
	v_add_f32_e32 v102, v88, v102
	v_and_b32_e32 v88, 0xffff0000, v98
	v_add_f32_e32 v98, v89, v88
	v_lshlrev_b32_e32 v88, 16, v99
	v_add_f32_e32 v103, v90, v88
	v_and_b32_e32 v88, 0xffff0000, v99
	v_add_f32_e32 v99, v91, v88
	v_lshlrev_b32_e32 v88, 16, v100
	v_add_f32_e32 v92, v92, v88
	v_and_b32_e32 v88, 0xffff0000, v100
	v_add_f32_e32 v93, v93, v88
	v_lshlrev_b32_e32 v88, 16, v101
	v_add_f32_e32 v94, v94, v88
	v_and_b32_e32 v88, 0xffff0000, v101
	v_add_f32_e32 v95, v95, v88
	v_add_u32_e32 v88, 0x12f90, v144
	ds_read_b128 v[88:91], v88
	s_waitcnt lgkmcnt(0)
	v_lshlrev_b32_e32 v100, 16, v88
	v_and_b32_e32 v88, 0xffff0000, v88
	v_add_f32_e32 v98, v98, v88
	v_lshlrev_b32_e32 v88, 16, v89
	v_add_f32_e32 v101, v103, v88
	v_and_b32_e32 v88, 0xffff0000, v89
	v_add_f32_e32 v99, v99, v88
	v_lshlrev_b32_e32 v88, 16, v90
	v_add_f32_e32 v100, v102, v100
	v_add_f32_e32 v102, v92, v88
	v_and_b32_e32 v88, 0xffff0000, v90
	v_add_f32_e32 v103, v93, v88
	v_lshlrev_b32_e32 v88, 16, v91
	v_add_f32_e32 v104, v94, v88
	v_and_b32_e32 v88, 0xffff0000, v91
	v_add_f32_e32 v105, v95, v88
	v_add_u32_e32 v88, 0x12d80, v144
	ds_read_b128 v[92:95], v88
	s_waitcnt lgkmcnt(0)
; __device__ __forceinline__ float bflo(unsigned u) { return __uint_as_float(u << 16); }
; __device__ __forceinline__ float bfhi(unsigned u) { return __uint_as_float(u & 0xffff0000u); }
; template <int W>
; __device__ __forceinline__ void pool_compute(const Params& p, int layer, int g, int dh, int tt, const int tidx) {
;     ...
;       for (int i = 0; i < W; ++i) {
;         u32x4 xv = *reinterpret_cast<const u32x4*>(xl + ks * 32 - i * PXS);
;         sum[0] += bflo(xv.x); sum[1] += bfhi(xv.x); sum[2] += bflo(xv.y); sum[3] += bfhi(xv.y);
;         sum[4] += bflo(xv.z); sum[5] += bfhi(xv.z); sum[6] += bflo(xv.w); sum[7] += bfhi(xv.w);
;       }
;       u32x4 bfr;
;       bfr.x = pack2(sum[0] * inv - bflo(x0.x), sum[1] * inv - bfhi(x0.x));
;       bfr.y = pack2(sum[2] * inv - bflo(x0.y), sum[3] * inv - bfhi(x0.y));
;       bfr.z = pack2(sum[4] * inv - bflo(x0.z), sum[5] * inv - bfhi(x0.z));
;       bfr.w = pack2(sum[6] * inv - bflo(x0.w), sum[7] * inv - bfhi(x0.w));
; #pragma unroll
;       for (int d = 0; d < 4; ++d) acc[d] = __builtin_amdgcn_mfma_f32_32x32x16_bf16(as_bf16x8(av[k4][d]), as_bf16x8(bfr), acc[d], 0, 0, 0);
	v_and_b32_e32 v89, 0xffff0000, v92
	v_lshlrev_b32_e32 v88, 16, v92
	v_add_f32_e32 v89, v98, v89
	v_lshlrev_b32_e32 v90, 16, v93
	v_and_b32_e32 v91, 0xffff0000, v93
	v_add_u32_e32 v98, 0x12b70, v144
	v_add_f32_e32 v88, v100, v88
	v_add_f32_e32 v90, v101, v90
	v_add_f32_e32 v91, v99, v91
	ds_read_b128 v[98:101], v98
	v_lshlrev_b32_e32 v92, 16, v94
	v_add_f32_e32 v92, v102, v92
	v_and_b32_e32 v93, 0xffff0000, v94
	v_add_f32_e32 v93, v103, v93
	s_waitcnt lgkmcnt(0)
	v_lshlrev_b32_e32 v102, 16, v98
	v_add_f32_e32 v102, v88, v102
	v_and_b32_e32 v88, 0xffff0000, v98
	v_add_f32_e32 v98, v89, v88
	v_lshlrev_b32_e32 v88, 16, v99
	v_add_f32_e32 v103, v90, v88
	v_and_b32_e32 v88, 0xffff0000, v99
	v_add_f32_e32 v99, v91, v88
	v_lshlrev_b32_e32 v88, 16, v100
	v_lshlrev_b32_e32 v94, 16, v95
	v_add_f32_e32 v92, v92, v88
	v_and_b32_e32 v88, 0xffff0000, v100
	v_add_f32_e32 v94, v104, v94
	v_and_b32_e32 v95, 0xffff0000, v95
	v_add_f32_e32 v93, v93, v88
	v_lshlrev_b32_e32 v88, 16, v101
	v_add_f32_e32 v95, v105, v95
	v_add_f32_e32 v94, v94, v88
	v_and_b32_e32 v88, 0xffff0000, v101
	v_add_f32_e32 v95, v95, v88
	v_add_u32_e32 v172, 0x12960, v144
	ds_read_b128 v[172:175], v172
	s_waitcnt lgkmcnt(0)
	v_add_u32_e32 v168, 0x12750, v144
	ds_read_b128 v[168:171], v168
	v_add_u32_e32 v88, 0x12540, v144
	ds_read_b128 v[88:91], v88
	v_lshlrev_b32_e32 v100, 16, v172
	v_and_b32_e32 v172, 0xffff0000, v172
	v_add_f32_e32 v98, v98, v172
	v_lshlrev_b32_e32 v172, 16, v173
	v_add_f32_e32 v101, v103, v172
	v_and_b32_e32 v172, 0xffff0000, v173
	v_add_f32_e32 v99, v99, v172
	v_lshlrev_b32_e32 v172, 16, v174
	v_add_f32_e32 v92, v92, v172
	v_and_b32_e32 v172, 0xffff0000, v174
	v_add_f32_e32 v93, v93, v172
	v_lshlrev_b32_e32 v172, 16, v175
	v_add_f32_e32 v94, v94, v172
	v_and_b32_e32 v172, 0xffff0000, v175
	v_add_f32_e32 v95, v95, v172
	v_add_f32_e32 v100, v102, v100
	s_waitcnt lgkmcnt(1)
	v_lshlrev_b32_e32 v102, 16, v168
	v_and_b32_e32 v168, 0xffff0000, v168
	v_add_f32_e32 v98, v98, v168
	v_lshlrev_b32_e32 v168, 16, v169
	v_add_f32_e32 v101, v101, v168
	v_and_b32_e32 v168, 0xffff0000, v169
	v_add_f32_e32 v99, v99, v168
	v_lshlrev_b32_e32 v168, 16, v170
	v_add_f32_e32 v92, v92, v168
	v_and_b32_e32 v168, 0xffff0000, v170
	v_add_f32_e32 v93, v93, v168
	v_lshlrev_b32_e32 v168, 16, v171
	v_add_f32_e32 v94, v94, v168
	v_and_b32_e32 v168, 0xffff0000, v171
	v_add_f32_e32 v95, v95, v168
	v_add_f32_e32 v100, v100, v102
	s_waitcnt lgkmcnt(0)
	v_lshlrev_b32_e32 v102, 16, v88
	v_and_b32_e32 v88, 0xffff0000, v88
	v_add_f32_e32 v103, v98, v88
	v_lshlrev_b32_e32 v88, 16, v89
	v_add_f32_e32 v104, v101, v88
	v_and_b32_e32 v88, 0xffff0000, v89
	v_add_u32_e32 v89, 0x12330, v144
	v_add_f32_e32 v102, v100, v102
	v_add_f32_e32 v105, v99, v88
	ds_read_b128 v[98:101], v89
	v_lshlrev_b32_e32 v88, 16, v90
	v_add_f32_e32 v106, v92, v88
	v_and_b32_e32 v88, 0xffff0000, v90
	v_add_f32_e32 v107, v93, v88
	v_lshlrev_b32_e32 v88, 16, v91
	v_add_f32_e32 v108, v94, v88
	v_and_b32_e32 v88, 0xffff0000, v91
	s_waitcnt lgkmcnt(0)
	v_lshlrev_b32_e32 v89, 16, v98
	v_and_b32_e32 v90, 0xffff0000, v98
	v_add_f32_e32 v88, v95, v88
	v_add_f32_e32 v89, v102, v89
	v_add_f32_e32 v90, v103, v90
	v_lshlrev_b32_e32 v91, 16, v99
	v_and_b32_e32 v92, 0xffff0000, v99
	v_lshlrev_b32_e32 v93, 16, v100
	v_and_b32_e32 v94, 0xffff0000, v100
	v_lshlrev_b32_e32 v95, 16, v101
	v_and_b32_e32 v98, 0xffff0000, v101
	v_add_f32_e32 v91, v104, v91
	v_add_f32_e32 v92, v105, v92
	v_add_f32_e32 v93, v106, v93
	v_add_f32_e32 v94, v107, v94
	v_add_f32_e32 v95, v108, v95
	v_add_f32_e32 v98, v88, v98
	v_fma_f32 v86, v135, v89, -v86
	v_fma_f32 v87, v135, v90, -v87
	v_cvt_pk_bf16_f32 v86, v86, v87
	v_fma_f32 v84, v135, v91, -v84
	v_fma_f32 v85, v135, v92, -v85
	v_cvt_pk_bf16_f32 v87, v84, v85
	v_fma_f32 v83, v135, v93, -v83
	v_fma_f32 v82, v135, v94, -v82
	v_cvt_pk_bf16_f32 v88, v83, v82
	v_fma_f32 v80, v135, v95, -v80
	v_fma_f32 v81, v135, v98, -v81
	v_cvt_pk_bf16_f32 v89, v80, v81
	s_nop 0
	v_mfma_f32_32x32x16_bf16 v[48:63], v[64:67], v[86:89], v[48:63]
	v_mfma_f32_32x32x16_bf16 v[32:47], v[68:71], v[86:89], v[32:47]
	v_mfma_f32_32x32x16_bf16 v[16:31], v[72:75], v[86:89], v[16:31]
	s_waitcnt vmcnt(0)
	v_mfma_f32_32x32x16_bf16 v[0:15], v[76:79], v[86:89], v[0:15]
	s_cbranch_scc1 .LBB0_185
; #define SCHED __builtin_amdgcn_sched_barrier(0)
; template <int W>
; __device__ __forceinline__ void pool_compute(const Params& p, int layer, int g, int dh, int tt, const int tidx) {
;     ...
;   u16* yo = yraw + (size_t)t * DM + g * 256;
;   f32x4 scv[4][4];
; #pragma unroll
;   for (int d = 0; d < 4; ++d)
; #pragma unroll
;     for (int rg = 0; rg < 4; ++rg) scv[d][rg] = *reinterpret_cast<const f32x4*>(psc + (dh * 4 + d) * 32 + 8 * rg + 4 * half);
;   SCHED;
; #pragma unroll
;   for (int d = 0; d < 4; ++d)
; #pragma unroll
;     for (int rg = 0; rg < 4; ++rg) {
;       int dd = (dh * 4 + d) * 32 + 8 * rg + 4 * half;
;       f32x4 sc = scv[d][rg];
;       u32x2 o = {pack2(acc[d][rg * 4 + 0] * sc[0], acc[d][rg * 4 + 1] * sc[1]), pack2(acc[d][rg * 4 + 2] * sc[2], acc[d][rg * 4 + 3] * sc[3])};
;       *reinterpret_cast<u32x2*>(yo + dd) = o;
;     }
	v_mov_b32_e32 v135, v163
	v_lshl_add_u64 v[64:65], s[78:79], 0, v[134:135]
	v_lshlrev_b32_e32 v66, 9, v138
	v_mov_b32_e32 v67, v163
	v_lshl_add_u64 v[126:127], v[64:65], 0, v[66:67]
	global_load_dwordx4 v[64:67], v[126:127], off offset:3072
	global_load_dwordx4 v[68:71], v[126:127], off offset:3104
	global_load_dwordx4 v[72:75], v[126:127], off offset:3136
	global_load_dwordx4 v[76:79], v[126:127], off offset:3168
	global_load_dwordx4 v[80:83], v[126:127], off offset:3200
	global_load_dwordx4 v[84:87], v[126:127], off offset:3232
	global_load_dwordx4 v[88:91], v[126:127], off offset:3264
	global_load_dwordx4 v[92:95], v[126:127], off offset:3296
	global_load_dwordx4 v[98:101], v[126:127], off offset:3328
	global_load_dwordx4 v[102:105], v[126:127], off offset:3360
	global_load_dwordx4 v[106:109], v[126:127], off offset:3392
	global_load_dwordx4 v[110:113], v[126:127], off offset:3424
	global_load_dwordx4 v[114:117], v[126:127], off offset:3456
	global_load_dwordx4 v[118:121], v[126:127], off offset:3488
	global_load_dwordx4 v[122:125], v[126:127], off offset:3520
	s_nop 0
	global_load_dwordx4 v[126:129], v[126:127], off offset:3552
	v_lshlrev_b32_e32 v130, 13, v140
	v_mov_b32_e32 v131, v163
	v_lshl_add_u64 v[130:131], s[86:87], 0, v[130:131]
	s_waitcnt vmcnt(15)
	v_mul_f32_e32 v48, v48, v64
	v_mul_f32_e32 v49, v49, v65
	v_cvt_pk_bf16_f32 v64, v48, v49
	v_mul_f32_e32 v48, v50, v66
	v_mul_f32_e32 v49, v51, v67
	v_cvt_pk_bf16_f32 v65, v48, v49
	v_lshlrev_b32_e32 v48, 3, v139
	v_lshl_or_b32 v48, v138, 8, v48
	v_mov_b32_e32 v49, v163
	v_lshl_add_u64 v[50:51], v[130:131], 0, v[48:49]
	s_mov_b64 s[12:13], 0x22900600
	v_lshl_add_u64 v[48:49], v[50:51], 0, s[12:13]
	s_mov_b32 s12, 0x22900000
	s_waitcnt vmcnt(11)
	v_mul_f32_e32 v32, v32, v80
	v_mul_f32_e32 v33, v33, v81
	s_waitcnt vmcnt(7)
	v_mul_f32_e32 v16, v16, v98
	v_mul_f32_e32 v17, v17, v99
	s_waitcnt vmcnt(3)
	v_mul_f32_e32 v0, v0, v114
	v_mul_f32_e32 v1, v1, v115
	v_add_co_u32_e32 v50, vcc, s12, v50
	v_cvt_pk_bf16_f32 v32, v32, v33
	v_mul_f32_e32 v33, v34, v82
	v_cvt_pk_bf16_f32 v16, v16, v17
	v_mul_f32_e32 v17, v18, v100
	v_cvt_pk_bf16_f32 v0, v0, v1
	v_mul_f32_e32 v1, v2, v116
	v_addc_co_u32_e32 v51, vcc, 0, v51, vcc
	v_mul_f32_e32 v34, v35, v83
	v_cvt_pk_bf16_f32 v33, v33, v34
	v_mul_f32_e32 v18, v19, v101
	v_cvt_pk_bf16_f32 v17, v17, v18
	v_mul_f32_e32 v2, v3, v117
	v_cvt_pk_bf16_f32 v1, v1, v2
	global_store_dwordx2 v[50:51], v[64:65], off offset:1536
	v_mul_f32_e32 v50, v52, v68
	v_mul_f32_e32 v51, v53, v69
	global_store_dwordx2 v[48:49], v[32:33], off offset:64
	v_mul_f32_e32 v32, v36, v84
	v_mul_f32_e32 v33, v37, v85
	global_store_dwordx2 v[48:49], v[16:17], off offset:128
	v_mul_f32_e32 v16, v20, v102
	v_mul_f32_e32 v17, v21, v103
	global_store_dwordx2 v[48:49], v[0:1], off offset:192
	s_waitcnt vmcnt(6)
	v_mul_f32_e32 v0, v4, v118
	v_mul_f32_e32 v1, v5, v119
	v_cvt_pk_bf16_f32 v50, v50, v51
	v_mul_f32_e32 v51, v54, v70
	v_cvt_pk_bf16_f32 v32, v32, v33
	v_mul_f32_e32 v33, v38, v86
	v_cvt_pk_bf16_f32 v16, v16, v17
	v_mul_f32_e32 v17, v22, v104
	v_cvt_pk_bf16_f32 v0, v0, v1
	v_mul_f32_e32 v1, v6, v120
	v_mul_f32_e32 v52, v55, v71
	v_cvt_pk_bf16_f32 v51, v51, v52
	v_mul_f32_e32 v34, v39, v87
	v_cvt_pk_bf16_f32 v33, v33, v34
	v_mul_f32_e32 v18, v23, v105
	v_cvt_pk_bf16_f32 v17, v17, v18
	v_mul_f32_e32 v2, v7, v121
	v_cvt_pk_bf16_f32 v1, v1, v2
	global_store_dwordx2 v[48:49], v[50:51], off offset:16
	v_mul_f32_e32 v50, v56, v72
	v_mul_f32_e32 v51, v57, v73
	global_store_dwordx2 v[48:49], v[32:33], off offset:80
	v_mul_f32_e32 v32, v40, v88
	v_mul_f32_e32 v33, v41, v89
	global_store_dwordx2 v[48:49], v[16:17], off offset:144
	v_mul_f32_e32 v16, v24, v106
	v_mul_f32_e32 v17, v25, v107
	global_store_dwordx2 v[48:49], v[0:1], off offset:208
	s_waitcnt vmcnt(9)
	v_mul_f32_e32 v0, v8, v122
	v_mul_f32_e32 v1, v9, v123
	v_cvt_pk_bf16_f32 v50, v50, v51
	v_mul_f32_e32 v51, v58, v74
	v_cvt_pk_bf16_f32 v32, v32, v33
	v_mul_f32_e32 v33, v42, v90
	v_cvt_pk_bf16_f32 v16, v16, v17
	v_mul_f32_e32 v17, v26, v108
	v_cvt_pk_bf16_f32 v0, v0, v1
	v_mul_f32_e32 v1, v10, v124
	v_mul_f32_e32 v52, v59, v75
	v_cvt_pk_bf16_f32 v51, v51, v52
	v_mul_f32_e32 v34, v43, v91
	v_cvt_pk_bf16_f32 v33, v33, v34
	v_mul_f32_e32 v18, v27, v109
	v_cvt_pk_bf16_f32 v17, v17, v18
	v_mul_f32_e32 v2, v11, v125
	v_cvt_pk_bf16_f32 v1, v1, v2
	global_store_dwordx2 v[48:49], v[50:51], off offset:32
	v_mul_f32_e32 v50, v60, v76
	v_mul_f32_e32 v51, v61, v77
	global_store_dwordx2 v[48:49], v[32:33], off offset:96
	v_mul_f32_e32 v32, v44, v92
	v_mul_f32_e32 v33, v45, v93
	global_store_dwordx2 v[48:49], v[16:17], off offset:160
	v_mul_f32_e32 v16, v28, v110
	v_mul_f32_e32 v17, v29, v111
	global_store_dwordx2 v[48:49], v[0:1], off offset:224
	s_waitcnt vmcnt(12)
	v_mul_f32_e32 v0, v12, v126
	v_mul_f32_e32 v1, v13, v127
	v_cvt_pk_bf16_f32 v50, v50, v51
	v_mul_f32_e32 v51, v62, v78
	v_cvt_pk_bf16_f32 v32, v32, v33
	v_mul_f32_e32 v33, v46, v94
	v_cvt_pk_bf16_f32 v16, v16, v17
	v_mul_f32_e32 v17, v30, v112
	v_cvt_pk_bf16_f32 v0, v0, v1
	v_mul_f32_e32 v1, v14, v128
	s_andn2_b64 s[8:9], s[8:9], exec
	v_mul_f32_e32 v52, v63, v79
	v_cvt_pk_bf16_f32 v51, v51, v52
	global_store_dwordx2 v[48:49], v[50:51], off offset:48
	v_mul_f32_e32 v34, v47, v95
	v_cvt_pk_bf16_f32 v33, v33, v34
	global_store_dwordx2 v[48:49], v[32:33], off offset:112
	v_mul_f32_e32 v18, v31, v113
	v_cvt_pk_bf16_f32 v17, v17, v18
	global_store_dwordx2 v[48:49], v[16:17], off offset:176
	v_mul_f32_e32 v2, v15, v129
	v_cvt_pk_bf16_f32 v1, v1, v2
	s_or_b64 exec, exec, s[10:11]
	s_and_saveexec_b64 s[10:11], s[8:9]
	s_xor_b64 s[8:9], exec, s[10:11]
	s_cbranch_execz .LBB0_190
